# helper waves: leaner table preparation (sigmoid work merged into the norm chain, next-input loads spread, other-half r loaded only when the bonus sum needs it, bonus work split over both directions)
# baseline (speedup 1.0000x reference)
;     __device__ __forceinline__ bf16* R(int i) const { return (bf16*)(ws + OFF_R0 + (size_t)i * RSZ); }
; __device__ __forceinline__ void phase_rwkv_scan(const Fr& F, int jr) {
;     ...
;         const int half = task & 1, h = (task >> 1) & 15, b = (task >> 5) & 3, s = task >> 7;
;         bf16* Yb = F.R(s);
;         const float* w0 = F.a->in[9] + (size_t)(jr * 2 + s) * D + h * 64; const float* a0 = F.a->in[12] + (size_t)(jr * 2 + s) * D + h * 64;
;         const float* kkw = F.a->in[15] + (size_t)jr * D + h * 64; const float* kaw = F.a->in[16] + (size_t)jr * D + h * 64;
;         f32x2 S01 = {0.f, 0.f}, S23 = {0.f, 0.f};
;         const int ks = 4 * l15, rloc = 4 * wave + lq;
;         const int pt = wave & 3, ht0 = (wave >> 2) * 2;
;         const int p1 = pt * 16 + l15;
;         const int p2 = tid >> 3, j8 = tid & 7, hk0 = 8 * j8;
;         bf16x8 Bw[2][2], Ba[2][2]; float w0v[2], a0v[2];
; #pragma unroll
;         for (int hh = 0; hh < 2; ++hh) { const int hk = (ht0 + hh) * 16 + l15, e = h * 64 + hk; w0v[hh] = w0[hk]; a0v[hh] = a0[hk];
; #pragma unroll
;             for (int kst = 0; kst < 2; ++kst) { Bw[hh][kst] = *(const bf16x8*)(L2T + ((size_t)s * D + e) * 64 + 32 * kst + 8 * lq); Ba[hh][kst] = *(const bf16x8*)(L2T + ((size_t)(2 + s) * D + e) * 64 + 32 * kst + 8 * lq); } }
;         float kkc[8], kac[8], rkc[8];
; #pragma unroll
;         for (int i = 0; i < 8; ++i) { kkc[i] = kkw[hk0 + i]; kac[i] = kaw[hk0 + i]; rkc[i] = F.a->in[17][(size_t)jr * D + h * 64 + hk0 + i]; }
;         float* Bon = (float*)(F.ws + OFF_R0 + 6 * RSZ + 16 * MiB);
;         bf16x8 Aw[2], Aa[2]; u32x4 kw, rw; u32x2 vw;
;         {   const size_t row1 = (size_t)b * TB + tokof(s, p1), row2 = (size_t)b * TB + tokof(s, p2);
; #pragma unroll
;             for (int kst = 0; kst < 2; ++kst) { Aw[kst] = *(const bf16x8*)(LM + row1 * 256 + 64 * s + 32 * kst + 8 * lq); Aa[kst] = *(const bf16x8*)(LM + row1 * 256 + 128 + 64 * s + 32 * kst + 8 * lq); }
;             kw = *(const u32x4*)(Kb + row2 * D + h * 64 + hk0); rw = *(const u32x4*)(Rb + row2 * D + h * 64 + hk0); vw = *(const u32x2*)(Vb + row2 * D + h * 64 + 32 * half + 4 * j8); }
.Lrw0_hdir0:
	s_mul_i32 s16, s7, 0x1100
	v_lshlrev_b32_e32 v221, 4, v217
	s_lshl_b32 s17, s15, 6
	v_lshl_add_u32 v219, v217, 3, s17
	s_xor_b32 s18, s17, 64
	v_lshl_add_u32 v220, v217, 3, s18
	s_lshl_b32 s17, s15, 7
	v_mul_u32_u24_e32 v197, 0x110, v216
	v_add_u32_e32 v197, s17, v197
	v_lshl_add_u32 v222, v217, 4, v197
	v_lshl_add_u32 v223, v217, 5, v197
	s_lshl_b32 s17, s6, 7
	s_add_u32 s20, s26, 0xde00000
	s_addc_u32 s21, s27, 0
	s_add_u32 s20, s20, s17
	s_addc_u32 s21, s21, 0
	s_lshl_b32 s17, s8, 7
	s_add_u32 s22, s26, 0xbc00000
	s_addc_u32 s23, s27, 0
	s_add_u32 s22, s22, s17
	s_addc_u32 s23, s23, 0
	s_add_u32 s24, s26, 0x9a00000
	s_addc_u32 s25, s27, 0
	s_add_u32 s24, s24, s17
	s_addc_u32 s25, s25, 0
	s_lshl_b32 s18, s9, 6
	s_add_i32 s17, s17, s18
	s_lshl_b32 s18, s15, 5
	s_add_i32 s17, s17, s18
	s_add_u32 s42, s26, 0x5600000
	s_addc_u32 s43, s27, 0
	s_add_u32 s42, s42, s17
	s_addc_u32 s43, s43, 0
	s_lshl_b32 s17, s8, 2
	s_add_u32 s44, s26, 0xee00000
	s_addc_u32 s45, s27, 0
	s_add_u32 s44, s44, s17
	s_addc_u32 s45, s45, 0
	s_or_b32 s17, s9, s15
	s_cmp_eq_u32 s17, 0
	s_cselect_b32 s32, 1, 0
	s_load_dwordx2 s[46:47], s[0:1], 0x48
	s_load_dwordx2 s[48:49], s[0:1], 0x60
	s_load_dwordx2 s[50:51], s[0:1], 0x78
	s_load_dwordx2 s[52:53], s[0:1], 0x80
	s_load_dwordx2 s[54:55], s[0:1], 0x88
	s_lshl_b32 s17, s8, 8
	s_lshl_b32 s18, s15, 7
	s_add_i32 s19, s17, s18
	v_lshl_add_u32 v198, v217, 4, s19
	s_xor_b32 s18, s18, 128
	s_add_i32 s19, s17, s18
	v_lshl_add_u32 v199, v217, 4, s19
	s_waitcnt lgkmcnt(0)
	s_lshl_b32 s17, s6, 12
	s_add_u32 s46, s46, s17
	s_addc_u32 s47, s47, 0
	s_add_u32 s48, s48, s17
	s_addc_u32 s49, s49, 0
	global_load_dwordx4 v[32:35], v198, s[46:47] offset:0
	global_load_dwordx4 v[40:43], v198, s[48:49] offset:0
	global_load_dwordx4 v[64:67], v198, s[52:53] offset:0
	global_load_dwordx4 v[36:39], v198, s[46:47] offset:64
	global_load_dwordx4 v[44:47], v198, s[48:49] offset:64
	global_load_dwordx4 v[68:71], v198, s[52:53] offset:64
	global_load_dwordx4 v[48:51], v198, s[50:51] offset:0
	global_load_dwordx4 v[72:75], v198, s[54:55] offset:0
	global_load_dwordx4 v[52:55], v198, s[50:51] offset:64
	global_load_dwordx4 v[76:79], v198, s[54:55] offset:64
	global_load_dwordx4 v[56:59], v199, s[50:51] offset:0
	global_load_dwordx4 v[80:83], v199, s[54:55] offset:0
	global_load_dwordx4 v[60:63], v199, s[50:51] offset:64
	global_load_dwordx4 v[84:87], v199, s[54:55] offset:64
	s_lshl_b32 s17, s8, 6
	s_lshl_b32 s18, s15, 5
	s_add_i32 s17, s17, s18
	v_add_u32_e32 v200, s17, v196
	v_lshlrev_b32_e32 v200, 7, v200
	v_add_u32_e32 v200, v200, v221
	s_lshl_b32 s17, s6, 17
	s_add_u32 s46, s26, 0x200000
	s_addc_u32 s47, s27, 0
	s_add_u32 s46, s46, s17
	s_addc_u32 s47, s47, 0
	s_add_u32 s48, s46, 0x40000
	s_addc_u32 s49, s47, 0
	global_load_dwordx4 v[0:3], v200, s[46:47] offset:0
	global_load_dwordx4 v[16:19], v200, s[48:49] offset:0
	global_load_dwordx4 v[4:7], v200, s[46:47] offset:64
	global_load_dwordx4 v[20:23], v200, s[48:49] offset:64
	global_load_dwordx4 v[8:11], v200, s[46:47] offset:2048
	global_load_dwordx4 v[24:27], v200, s[48:49] offset:2048
	global_load_dwordx4 v[12:15], v200, s[46:47] offset:2112
	global_load_dwordx4 v[28:31], v200, s[48:49] offset:2112
	s_mov_b32 s10, 0
	s_mov_b32 s11, 0
	s_lshl_b32 s17, s10, 5
	s_cmp_lt_u32 s10, 8
	s_movk_i32 s18, 0x11ff
	s_cselect_b32 s18, 0xff, s18
	s_sub_i32 s18, s18, s17
	s_cmp_eq_u32 s6, 0
	s_cselect_b32 s17, s17, s18
	s_add_i32 s17, s17, s16
	v_add_u32_e32 v231, s17, v218
	v_lshl_add_u32 v226, v231, 9, v221
	v_lshl_add_u32 v227, v231, 11, v219
	v_lshl_add_u32 v228, v231, 11, v220
	v_lshlrev_b32_e32 v229, 3, v217
	v_lshl_add_u32 v229, v231, 11, v229
	v_lshlrev_b32_e32 v230, 6, v231
	global_load_dwordx4 v[88:91], v226, s[20:21]
	global_load_dwordx4 v[92:95], v226, s[20:21] offset:64
	global_load_dwordx4 v[96:99], v226, s[20:21] offset:256
	global_load_dwordx4 v[100:103], v226, s[20:21] offset:320
	global_load_dwordx2 v[104:105], v227, s[22:23] offset:0
	global_load_dwordx2 v[106:107], v227, s[22:23] offset:32
	global_load_dwordx2 v[108:109], v228, s[22:23] offset:0
	global_load_dwordx2 v[110:111], v228, s[22:23] offset:32
	global_load_dwordx2 v[112:113], v227, s[24:25] offset:0
	global_load_dwordx2 v[114:115], v227, s[24:25] offset:32
	global_load_dwordx2 v[116:117], v228, s[24:25] offset:0
	global_load_dwordx2 v[118:119], v228, s[24:25] offset:32
	global_load_dwordx2 v[120:121], v229, s[42:43]
	v_mov_b32_e32 v224, v222
	v_mov_b32_e32 v225, v223
	v_mov_b32_e32 v202, v230
	s_mov_b32 s89, 0
	s_mov_b32 s88, s32
	s_cmp_eq_u32 s89, 0
	s_cbranch_scc1 .Lrw0_hwall0
	s_waitcnt vmcnt(1)
	s_branch .Lrw0_hwdone0

; __device__ __forceinline__ float sigm(float x) { return __builtin_amdgcn_rcpf(1.f + __expf(-x)); }
; __device__ __forceinline__ void phase_rwkv_scan(const Fr& F, int jr) {
;     ...
;             for (int hh = 0; hh < 2; ++hh) {
;                 const int hk = (ht0 + hh) * 16 + l15;
;                 f32x4 cw = {0.f, 0.f, 0.f, 0.f}, ca = {0.f, 0.f, 0.f, 0.f};
; #pragma unroll
;                 for (int kst = 0; kst < 2; ++kst) { cw = __builtin_amdgcn_mfma_f32_16x16x32_bf16(Aw[kst], Bw[hh][kst], cw, 0, 0, 0); ca = __builtin_amdgcn_mfma_f32_16x16x32_bf16(Aa[kst], Ba[hh][kst], ca, 0, 0, 0); }
; #pragma unroll
;                 for (int reg = 0; reg < 4; ++reg) { const int pp = pt * 16 + lq * 4 + reg;
;                     Wv[pp * 64 + hk] = __expf(-0.60653066f * sigm(w0v[hh] + cw[reg]));
;                     Av[pp * 64 + hk] = sigm(a0v[hh] + ca[reg]); }
;             }
;             LDS_BAR();
;             {
;                 const float kr[8] = {lo_bf(kw.x), hi_bf(kw.x), lo_bf(kw.y), hi_bf(kw.y), lo_bf(kw.z), hi_bf(kw.z), lo_bf(kw.w), hi_bf(kw.w)};
;                 const float rr[8] = {lo_bf(rw.x), hi_bf(rw.x), lo_bf(rw.y), hi_bf(rw.y), lo_bf(rw.z), hi_bf(rw.z), lo_bf(rw.w), hi_bf(rw.w)};
;                 float kq[8]; float ss = 0.f, bon = 0.f;
; #pragma unroll
;                 for (int i = 0; i < 8; ++i) { kq[i] = kr[i] * kkc[i]; ss += kq[i] * kq[i]; bon += rr[i] * kr[i] * rkc[i]; }
;                 ss += dppf<0xB1>(ss); ss += dppf<0x4E>(ss); ss += dppf<0x141>(ss); bon += dppf<0xB1>(bon); bon += dppf<0x4E>(bon); bon += dppf<0x141>(bon);
;                 if (s == 0 && half == 0 && j8 == 0) Bon[((size_t)b * TB + tokof(s, chunk * 64 + p2)) * 16 + h] = bon;
;                 const float inv = 1.f / fmaxf(sqrtf(ss), 1e-12f);
;                 const f32x4 av0 = *(const f32x4*)(Av + p2 * 64 + hk0), av1 = *(const f32x4*)(Av + p2 * 64 + hk0 + 4);
;                 const float av[8] = {av0.x, av0.y, av0.z, av0.w, av1.x, av1.y, av1.z, av1.w};
;                 float o1[8], o2[8], o3[8];
; #pragma unroll
;                 for (int i = 0; i < 8; ++i) { const float kkv = kq[i] * inv; o1[i] = kkv; o2[i] = kkv * av[i]; o3[i] = kr[i] * (1.f + (av[i] - 1.f) * kac[i]); }
;                 const int o = p2 * 64 + hk0;
;                 *(f32x4*)(KK + o) = (f32x4){o1[0], o1[1], o1[2], o1[3]}; *(f32x4*)(KK + o + 4) = (f32x4){o1[4], o1[5], o1[6], o1[7]};
.Lrw0_hwdone0:
	s_add_i32 s10, s10, 1
	s_min_u32 s19, s10, 135
	s_lshl_b32 s17, s19, 5
	s_cmp_lt_u32 s19, 8
	s_movk_i32 s18, 0x11ff
	s_cselect_b32 s18, 0xff, s18
	s_sub_i32 s18, s18, s17
	s_cmp_eq_u32 s6, 0
	s_cselect_b32 s17, s17, s18
	s_add_i32 s17, s17, s16
	v_add_u32_e32 v231, s17, v218
	v_lshl_add_u32 v226, v231, 9, v221
	v_lshl_add_u32 v227, v231, 11, v219
	v_lshl_add_u32 v228, v231, 11, v220
	v_lshlrev_b32_e32 v229, 3, v217
	v_lshl_add_u32 v229, v231, 11, v229
	v_lshlrev_b32_e32 v230, 6, v231
	v_mfma_f32_16x16x32_bf16 v[136:139], v[0:3], v[88:91], 0
	v_mfma_f32_16x16x32_bf16 v[136:139], v[4:7], v[92:95], v[136:139]
	v_mfma_f32_16x16x32_bf16 v[140:143], v[8:11], v[88:91], 0
	v_mfma_f32_16x16x32_bf16 v[140:143], v[12:15], v[92:95], v[140:143]
	v_mfma_f32_16x16x32_bf16 v[144:147], v[16:19], v[96:99], 0
	v_mfma_f32_16x16x32_bf16 v[144:147], v[20:23], v[100:103], v[144:147]
	v_mfma_f32_16x16x32_bf16 v[148:151], v[24:27], v[96:99], 0
	v_mfma_f32_16x16x32_bf16 v[148:151], v[28:31], v[100:103], v[148:151]
	v_lshlrev_b32_e32 v168, 16, v112
	v_and_b32_e32 v169, 0xffff0000, v112
	v_lshlrev_b32_e32 v170, 16, v113
	v_and_b32_e32 v171, 0xffff0000, v113
	v_lshlrev_b32_e32 v172, 16, v114
	v_and_b32_e32 v173, 0xffff0000, v114
	v_lshlrev_b32_e32 v174, 16, v115
	v_and_b32_e32 v175, 0xffff0000, v115
	global_load_dwordx4 v[88:91], v226, s[20:21]
	ds_write_b128 v224, v[168:171] offset:34816
	ds_write_b128 v224, v[172:175] offset:34880
	v_lshlrev_b32_e32 v152, 16, v104
	v_and_b32_e32 v153, 0xffff0000, v104
	v_lshlrev_b32_e32 v154, 16, v105
	v_and_b32_e32 v155, 0xffff0000, v105
	global_load_dwordx2 v[112:113], v227, s[24:25] offset:0
	v_lshlrev_b32_e32 v156, 16, v106
	v_and_b32_e32 v157, 0xffff0000, v106
	v_lshlrev_b32_e32 v158, 16, v107
	v_and_b32_e32 v159, 0xffff0000, v107
	global_load_dwordx4 v[92:95], v226, s[20:21] offset:64
	v_lshlrev_b32_e32 v160, 16, v108
	v_and_b32_e32 v161, 0xffff0000, v108
	v_lshlrev_b32_e32 v162, 16, v109
	v_and_b32_e32 v163, 0xffff0000, v109
	global_load_dwordx2 v[114:115], v227, s[24:25] offset:32
	v_lshlrev_b32_e32 v164, 16, v110
	v_and_b32_e32 v165, 0xffff0000, v110
	v_lshlrev_b32_e32 v166, 16, v111
	v_and_b32_e32 v167, 0xffff0000, v111
	global_load_dwordx4 v[96:99], v226, s[20:21] offset:256
	v_lshlrev_b32_e32 v192, 16, v120
	v_and_b32_e32 v193, 0xffff0000, v120
	v_lshlrev_b32_e32 v194, 16, v121
	v_and_b32_e32 v195, 0xffff0000, v121
	global_load_dwordx2 v[104:105], v227, s[22:23] offset:0
	v_pk_mul_f32 v[176:177], v[152:153], v[48:49]
	v_pk_mul_f32 v[178:179], v[154:155], v[50:51]
	v_pk_mul_f32 v[180:181], v[156:157], v[52:53]
	v_pk_mul_f32 v[182:183], v[158:159], v[54:55]
	global_load_dwordx4 v[100:103], v226, s[20:21] offset:320
	v_pk_mul_f32 v[184:185], v[160:161], v[56:57]
	v_pk_mul_f32 v[186:187], v[162:163], v[58:59]
	v_pk_mul_f32 v[188:189], v[164:165], v[60:61]
	v_pk_mul_f32 v[190:191], v[166:167], v[62:63]
	global_load_dwordx2 v[106:107], v227, s[22:23] offset:32
	v_pk_mul_f32 v[196:197], v[176:177], v[176:177]
	v_pk_mul_f32 v[198:199], v[178:179], v[178:179]
	v_pk_fma_f32 v[196:197], v[180:181], v[180:181], v[196:197]
	v_pk_fma_f32 v[198:199], v[182:183], v[182:183], v[198:199]
	v_pk_fma_f32 v[196:197], v[184:185], v[184:185], v[196:197]
	v_pk_fma_f32 v[198:199], v[186:187], v[186:187], v[198:199]
	global_load_dwordx2 v[108:109], v228, s[22:23] offset:0
	v_pk_fma_f32 v[196:197], v[188:189], v[188:189], v[196:197]
	v_pk_fma_f32 v[198:199], v[190:191], v[190:191], v[198:199]
	global_load_dwordx2 v[120:121], v229, s[42:43]
	v_pk_add_f32 v[196:197], v[196:197], v[198:199]
	v_mov_b32_e32 v184, v192
	v_mov_b32_e32 v185, v193
	v_mov_b32_e32 v186, v193
	v_mov_b32_e32 v187, v192
	v_mov_b32_e32 v188, v194
	v_mov_b32_e32 v189, v195
	v_mov_b32_e32 v190, v195
	v_mov_b32_e32 v191, v194
	ds_write_b128 v225, v[184:187] offset:43520
	global_load_dwordx2 v[110:111], v228, s[22:23] offset:32
	ds_write_b128 v225, v[188:191] offset:43536
	s_cmp_eq_u32 s88, 0
	s_cbranch_scc1 .Lrw0_hnbc0
	v_mul_f32_e32 v208, v168, v152
	v_mul_f32_e32 v209, v169, v153
	v_mul_f32_e32 v210, v170, v154
	v_mul_f32_e32 v211, v171, v155
	v_mul_f32_e32 v234, v72, v208
	v_fmac_f32_e32 v234, v73, v209
	v_fmac_f32_e32 v234, v74, v210
	v_fmac_f32_e32 v234, v75, v211
	v_mul_f32_e32 v208, v172, v156
	v_mul_f32_e32 v209, v173, v157
	v_mul_f32_e32 v210, v174, v158
	v_mul_f32_e32 v211, v175, v159
	v_fmac_f32_e32 v234, v76, v208
	v_fmac_f32_e32 v234, v77, v209
	v_fmac_f32_e32 v234, v78, v210
	v_fmac_f32_e32 v234, v79, v211
	v_lshlrev_b32_e32 v204, 16, v116
	v_and_b32_e32 v205, 0xffff0000, v116
	v_lshlrev_b32_e32 v206, 16, v117
	v_and_b32_e32 v207, 0xffff0000, v117
	v_mul_f32_e32 v208, v204, v160
	v_mul_f32_e32 v209, v205, v161
	v_mul_f32_e32 v210, v206, v162
	v_mul_f32_e32 v211, v207, v163
	v_fmac_f32_e32 v234, v80, v208
	v_fmac_f32_e32 v234, v81, v209
	v_fmac_f32_e32 v234, v82, v210
	v_fmac_f32_e32 v234, v83, v211
	v_lshlrev_b32_e32 v204, 16, v118
	v_and_b32_e32 v205, 0xffff0000, v118
	v_lshlrev_b32_e32 v206, 16, v119
	v_and_b32_e32 v207, 0xffff0000, v119
	v_mul_f32_e32 v208, v204, v164
	v_mul_f32_e32 v209, v205, v165
	v_mul_f32_e32 v210, v206, v166
	v_mul_f32_e32 v211, v207, v167
	v_fmac_f32_e32 v234, v84, v208
	v_fmac_f32_e32 v234, v85, v209
	v_fmac_f32_e32 v234, v86, v210
	v_fmac_f32_e32 v234, v87, v211
.Lrw0_hnbc0:
	v_add_f32_e32 v232, v196, v197
	s_and_b32 s17, s10, s32
	s_xor_b32 s17, s17, s32
	s_cmp_eq_u32 s17, 0
	s_cbranch_scc1 .Lrw0_hnr0
	global_load_dwordx2 v[116:117], v228, s[24:25] offset:0
	global_load_dwordx2 v[118:119], v228, s[24:25] offset:32
; __device__ __forceinline__ void phase_rwkv_scan(const Fr& F, int jr) {
;     ...
;                 for (int reg = 0; reg < 4; ++reg) { const int pp = pt * 16 + lq * 4 + reg;
;                     Wv[pp * 64 + hk] = __expf(-0.60653066f * sigm(w0v[hh] + cw[reg]));
;                     Av[pp * 64 + hk] = sigm(a0v[hh] + ca[reg]); }
;             }
;             LDS_BAR();
;             {
;                 const float kr[8] = {lo_bf(kw.x), hi_bf(kw.x), lo_bf(kw.y), hi_bf(kw.y), lo_bf(kw.z), hi_bf(kw.z), lo_bf(kw.w), hi_bf(kw.w)};
;                 const float rr[8] = {lo_bf(rw.x), hi_bf(rw.x), lo_bf(rw.y), hi_bf(rw.y), lo_bf(rw.z), hi_bf(rw.z), lo_bf(rw.w), hi_bf(rw.w)};
;                 float kq[8]; float ss = 0.f, bon = 0.f;
; #pragma unroll
;                 for (int i = 0; i < 8; ++i) { kq[i] = kr[i] * kkc[i]; ss += kq[i] * kq[i]; bon += rr[i] * kr[i] * rkc[i]; }
;                 ss += dppf<0xB1>(ss); ss += dppf<0x4E>(ss); ss += dppf<0x141>(ss); bon += dppf<0xB1>(bon); bon += dppf<0x4E>(bon); bon += dppf<0x141>(bon);
;                 if (s == 0 && half == 0 && j8 == 0) Bon[((size_t)b * TB + tokof(s, chunk * 64 + p2)) * 16 + h] = bon;
;                 const float inv = 1.f / fmaxf(sqrtf(ss), 1e-12f);
;                 const f32x4 av0 = *(const f32x4*)(Av + p2 * 64 + hk0), av1 = *(const f32x4*)(Av + p2 * 64 + hk0 + 4);
;                 const float av[8] = {av0.x, av0.y, av0.z, av0.w, av1.x, av1.y, av1.z, av1.w};
;                 float o1[8], o2[8], o3[8];
; #pragma unroll
;                 for (int i = 0; i < 8; ++i) { const float kkv = kq[i] * inv; o1[i] = kkv; o2[i] = kkv * av[i]; o3[i] = kr[i] * (1.f + (av[i] - 1.f) * kac[i]); }
;                 const int o = p2 * 64 + hk0;
;                 *(f32x4*)(KK + o) = (f32x4){o1[0], o1[1], o1[2], o1[3]}; *(f32x4*)(KK + o + 4) = (f32x4){o1[4], o1[5], o1[6], o1[7]};
;                 *(f32x4*)(Bv + o) = (f32x4){o2[0], o2[1], o2[2], o2[3]}; *(f32x4*)(Bv + o + 4) = (f32x4){o2[4], o2[5], o2[6], o2[7]};
;                 *(f32x4*)(KD + o) = (f32x4){o3[0], o3[1], o3[2], o3[3]}; *(f32x4*)(KD + o + 4) = (f32x4){o3[4], o3[5], o3[6], o3[7]};
;                 *(f32x4*)(Rr + o) = (f32x4){rr[0], rr[1], rr[2], rr[3]}; *(f32x4*)(Rr + o + 4) = (f32x4){rr[4], rr[5], rr[6], rr[7]};
;                 *(f32x4*)(Vv + p2 * 32 + 4 * j8) = (f32x4){lo_bf(vw.x), hi_bf(vw.x), lo_bf(vw.y), hi_bf(vw.y)};
;             }
.Lrw0_hnr0:
	v_mov_b32_e32 v196, v232
	v_pk_add_f32 v[136:137], v[32:33], v[136:137]
	v_pk_add_f32 v[138:139], v[34:35], v[138:139]
	v_pk_add_f32 v[144:145], v[40:41], v[144:145]
	v_permlane16_swap_b32_e32 v232, v196
	v_pk_add_f32 v[146:147], v[42:43], v[146:147]
	v_pk_add_f32 v[140:141], v[36:37], v[140:141]
	v_pk_add_f32 v[142:143], v[38:39], v[142:143]
	v_add_f32_e32 v232, v232, v196
	v_pk_add_f32 v[148:149], v[44:45], v[148:149]
	v_mov_b32_e32 v196, v232
	v_pk_add_f32 v[150:151], v[46:47], v[150:151]
	v_pk_mul_f32 v[136:137], v[136:137], v[122:123]
	v_pk_mul_f32 v[138:139], v[138:139], v[122:123]
	v_permlane32_swap_b32_e32 v232, v196
	v_pk_mul_f32 v[144:145], v[144:145], v[122:123]
	v_pk_mul_f32 v[146:147], v[146:147], v[122:123]
	v_pk_mul_f32 v[140:141], v[140:141], v[122:123]
	v_add_f32_e32 v232, v232, v196
	v_pk_mul_f32 v[142:143], v[142:143], v[122:123]
	v_mul_f32_e32 v197, 0x4f800000, v232
	v_pk_mul_f32 v[148:149], v[148:149], v[122:123]
	v_mov_b32_e32 v198, 0xf800000
	v_pk_mul_f32 v[150:151], v[150:151], v[122:123]
	v_cmp_gt_f32_e32 vcc, v198, v232
	v_exp_f32_e32 v136, v136
	v_exp_f32_e32 v137, v137
	v_exp_f32_e32 v138, v138
	v_cndmask_b32_e32 v196, v232, v197, vcc
	v_exp_f32_e32 v139, v139
	v_sqrt_f32_e32 v197, v196
	v_exp_f32_e32 v144, v144
	v_exp_f32_e32 v145, v145
	v_add_u32_e32 v198, -1, v197
	v_exp_f32_e32 v146, v146
	v_fma_f32 v200, -v198, v197, v196
	v_exp_f32_e32 v147, v147
	v_add_u32_e32 v199, 1, v197
	v_exp_f32_e32 v140, v140
	v_cmp_ge_f32_e64 s[56:57], 0, v200
	v_exp_f32_e32 v141, v141
	v_exp_f32_e32 v142, v142
	v_exp_f32_e32 v143, v143
	v_cndmask_b32_e64 v198, v197, v198, s[56:57]
	v_exp_f32_e32 v148, v148
	v_fma_f32 v197, -v199, v197, v196
	v_exp_f32_e32 v149, v149
	v_cmp_lt_f32_e64 s[56:57], 0, v197
	v_exp_f32_e32 v150, v150
	v_exp_f32_e32 v151, v151
	v_pk_add_f32 v[136:137], v[136:137], 1.0 op_sel_hi:[1,0]
	v_cndmask_b32_e64 v197, v198, v199, s[56:57]
	v_pk_add_f32 v[138:139], v[138:139], 1.0 op_sel_hi:[1,0]
	v_mul_f32_e32 v198, 0x37800000, v197
	v_pk_add_f32 v[144:145], v[144:145], 1.0 op_sel_hi:[1,0]
	v_cndmask_b32_e32 v197, v197, v198, vcc
	v_pk_add_f32 v[146:147], v[146:147], 1.0 op_sel_hi:[1,0]
	v_mov_b32_e32 v198, 0x260
	v_pk_add_f32 v[140:141], v[140:141], 1.0 op_sel_hi:[1,0]
	v_cmp_class_f32_e32 vcc, v196, v198
	v_pk_add_f32 v[142:143], v[142:143], 1.0 op_sel_hi:[1,0]
	v_pk_add_f32 v[148:149], v[148:149], 1.0 op_sel_hi:[1,0]
	v_pk_add_f32 v[150:151], v[150:151], 1.0 op_sel_hi:[1,0]
	v_cndmask_b32_e32 v196, v197, v196, vcc
	v_rcp_f32_e32 v136, v136
	v_max_f32_e32 v196, 0x2b8cbccc, v196
	v_rcp_f32_e32 v137, v137
	v_div_scale_f32 v197, s[56:57], v196, v196, 1.0
	v_rcp_f32_e32 v138, v138
	v_rcp_f32_e32 v198, v197
	v_rcp_f32_e32 v139, v139
	v_rcp_f32_e32 v144, v144
	v_fma_f32 v199, -v197, v198, 1.0
	v_rcp_f32_e32 v145, v145
	v_fmac_f32_e32 v198, v199, v198
	v_rcp_f32_e32 v146, v146
	v_div_scale_f32 v199, vcc, 1.0, v196, 1.0
	v_rcp_f32_e32 v147, v147
	v_mul_f32_e32 v200, v199, v198
	v_rcp_f32_e32 v140, v140
	v_fma_f32 v201, -v197, v200, v199
	v_rcp_f32_e32 v141, v141
	v_fmac_f32_e32 v200, v201, v198
	v_rcp_f32_e32 v142, v142
	v_fma_f32 v197, -v197, v200, v199
	v_rcp_f32_e32 v143, v143
	v_rcp_f32_e32 v148, v148
	v_div_fmas_f32 v197, v197, v198, v200
	v_rcp_f32_e32 v149, v149
	v_div_fixup_f32 v232, v197, v196, 1.0
	v_rcp_f32_e32 v150, v150
	v_rcp_f32_e32 v151, v151
	v_pk_mul_f32 v[136:137], v[136:137], v[124:125]
	v_pk_mul_f32 v[138:139], v[138:139], v[124:125]
	v_pk_mul_f32 v[140:141], v[140:141], v[124:125]
	v_pk_mul_f32 v[142:143], v[142:143], v[124:125]
	v_pk_mul_f32 v[136:137], v[136:137], v[126:127]
	v_pk_mul_f32 v[138:139], v[138:139], v[126:127]
	v_pk_mul_f32 v[140:141], v[140:141], v[126:127]
	v_pk_mul_f32 v[142:143], v[142:143], v[126:127]
	v_exp_f32_e32 v136, v136
	v_exp_f32_e32 v137, v137
	v_exp_f32_e32 v138, v138
	v_exp_f32_e32 v139, v139
	v_exp_f32_e32 v140, v140
	v_exp_f32_e32 v141, v141
	v_exp_f32_e32 v142, v142
	v_exp_f32_e32 v143, v143
	s_nop 0
	ds_write_b128 v224, v[136:139] offset:0
	ds_write_b128 v224, v[140:143] offset:64
	v_pk_mul_f32 v[204:205], v[176:177], v[232:233] op_sel_hi:[1,0]
	v_pk_mul_f32 v[206:207], v[178:179], v[232:233] op_sel_hi:[1,0]
	v_pk_add_f32 v[212:213], v[144:145], -1.0 op_sel_hi:[1,0]
	v_pk_add_f32 v[214:215], v[146:147], -1.0 op_sel_hi:[1,0]
	v_pk_mul_f32 v[208:209], v[204:205], v[144:145]
	v_pk_mul_f32 v[210:211], v[206:207], v[146:147]
	v_pk_fma_f32 v[212:213], v[64:65], v[212:213], 1.0 op_sel_hi:[1,1,0]
	v_pk_fma_f32 v[214:215], v[66:67], v[214:215], 1.0 op_sel_hi:[1,1,0]
	ds_write_b128 v224, v[204:207] offset:8704
	v_pk_mul_f32 v[212:213], v[212:213], v[152:153]
	v_pk_mul_f32 v[214:215], v[214:215], v[154:155]
	ds_write_b128 v224, v[208:211] offset:17408
	ds_write_b128 v224, v[212:215] offset:26112
	v_pk_mul_f32 v[184:185], v[180:181], v[232:233] op_sel_hi:[1,0]
	v_pk_mul_f32 v[186:187], v[182:183], v[232:233] op_sel_hi:[1,0]
	v_pk_add_f32 v[160:161], v[148:149], -1.0 op_sel_hi:[1,0]
	v_pk_add_f32 v[162:163], v[150:151], -1.0 op_sel_hi:[1,0]
	v_pk_mul_f32 v[188:189], v[184:185], v[148:149]
	v_pk_mul_f32 v[190:191], v[186:187], v[150:151]
	v_pk_fma_f32 v[160:161], v[68:69], v[160:161], 1.0 op_sel_hi:[1,1,0]
	v_pk_fma_f32 v[162:163], v[70:71], v[162:163], 1.0 op_sel_hi:[1,1,0]
	ds_write_b128 v224, v[184:187] offset:8768
	v_pk_mul_f32 v[160:161], v[160:161], v[156:157]
	v_pk_mul_f32 v[162:163], v[162:163], v[158:159]
	ds_write_b128 v224, v[188:191] offset:17472
	ds_write_b128 v224, v[160:163] offset:26176
	s_cmp_eq_u32 s88, 0
	s_cbranch_scc1 .Lrw0_hnb0
	v_mov_b32_e32 v196, v234
	s_nop 1
	v_permlane16_swap_b32_e32 v234, v196
	s_nop 1
	v_add_f32_e32 v234, v234, v196
	v_mov_b32_e32 v196, v234
	s_nop 1
	v_permlane32_swap_b32_e32 v234, v196
	s_nop 1
	v_add_f32_e32 v234, v234, v196
	v_cmp_gt_u32_e32 vcc, 16, v130
	s_and_saveexec_b64 s[56:57], vcc
	global_store_dword v202, v234, s[44:45]
	s_mov_b64 exec, s[56:57]
.Lrw0_hnb0:
	s_mov_b32 s89, s88
	s_waitcnt lgkmcnt(0)
	s_barrier
.Lrw0_hhc:
	s_cmp_lt_u32 s10, 136
	s_cbranch_scc0 .Lrw0_hlast
	s_xor_b32 s11, s11, 0xcc00
	v_add_u32_e32 v224, s11, v222
	v_add_u32_e32 v225, s11, v223
	v_mov_b32_e32 v202, v230
	s_and_b32 s17, s10, 1
	s_xor_b32 s17, s17, 1
	s_and_b32 s88, s32, s17
	s_cmp_eq_u32 s89, 0
	s_cbranch_scc1 .Lrw0_hwall1
	s_waitcnt vmcnt(1)
	s_branch .Lrw0_hwdone1

; template <int CTRL> __device__ __forceinline__ float dppf(float x) { return __builtin_bit_cast(float, __builtin_amdgcn_update_dpp(0, __builtin_bit_cast(int, x), CTRL, 0xF, 0xF, false)); }
; __device__ __forceinline__ void phase_rwkv_scan(const Fr& F, int jr) {
;     ...
;                 for (int i = 0; i < 8; ++i) { kq[i] = kr[i] * kkc[i]; ss += kq[i] * kq[i]; bon += rr[i] * kr[i] * rkc[i]; }
;                 ss += dppf<0xB1>(ss); ss += dppf<0x4E>(ss); ss += dppf<0x141>(ss); bon += dppf<0xB1>(bon); bon += dppf<0x4E>(bon); bon += dppf<0x141>(bon);
;                 if (s == 0 && half == 0 && j8 == 0) Bon[((size_t)b * TB + tokof(s, chunk * 64 + p2)) * 16 + h] = bon;
.Lrw0_hnb1:
	s_mov_b32 s89, s88
	s_waitcnt lgkmcnt(0)
	s_barrier
	s_branch .Lrw0_hhc

;     __device__ __forceinline__ bf16* R(int i) const { return (bf16*)(ws + OFF_R0 + (size_t)i * RSZ); }
; __device__ __forceinline__ void phase_rwkv_scan(const Fr& F, int jr) {
;     ...
;         const int half = task & 1, h = (task >> 1) & 15, b = (task >> 5) & 3, s = task >> 7;
;         bf16* Yb = F.R(s);
;         const float* w0 = F.a->in[9] + (size_t)(jr * 2 + s) * D + h * 64; const float* a0 = F.a->in[12] + (size_t)(jr * 2 + s) * D + h * 64;
;         const float* kkw = F.a->in[15] + (size_t)jr * D + h * 64; const float* kaw = F.a->in[16] + (size_t)jr * D + h * 64;
;         f32x2 S01 = {0.f, 0.f}, S23 = {0.f, 0.f};
;         const int ks = 4 * l15, rloc = 4 * wave + lq;
;         const int pt = wave & 3, ht0 = (wave >> 2) * 2;
;         const int p1 = pt * 16 + l15;
;         const int p2 = tid >> 3, j8 = tid & 7, hk0 = 8 * j8;
;         bf16x8 Bw[2][2], Ba[2][2]; float w0v[2], a0v[2];
; #pragma unroll
;         for (int hh = 0; hh < 2; ++hh) { const int hk = (ht0 + hh) * 16 + l15, e = h * 64 + hk; w0v[hh] = w0[hk]; a0v[hh] = a0[hk];
; #pragma unroll
;             for (int kst = 0; kst < 2; ++kst) { Bw[hh][kst] = *(const bf16x8*)(L2T + ((size_t)s * D + e) * 64 + 32 * kst + 8 * lq); Ba[hh][kst] = *(const bf16x8*)(L2T + ((size_t)(2 + s) * D + e) * 64 + 32 * kst + 8 * lq); } }
;         float kkc[8], kac[8], rkc[8];
; #pragma unroll
;         for (int i = 0; i < 8; ++i) { kkc[i] = kkw[hk0 + i]; kac[i] = kaw[hk0 + i]; rkc[i] = F.a->in[17][(size_t)jr * D + h * 64 + hk0 + i]; }
;         float* Bon = (float*)(F.ws + OFF_R0 + 6 * RSZ + 16 * MiB);
;         bf16x8 Aw[2], Aa[2]; u32x4 kw, rw; u32x2 vw;
;         {   const size_t row1 = (size_t)b * TB + tokof(s, p1), row2 = (size_t)b * TB + tokof(s, p2);
; #pragma unroll
;             for (int kst = 0; kst < 2; ++kst) { Aw[kst] = *(const bf16x8*)(LM + row1 * 256 + 64 * s + 32 * kst + 8 * lq); Aa[kst] = *(const bf16x8*)(LM + row1 * 256 + 128 + 64 * s + 32 * kst + 8 * lq); }
;             kw = *(const u32x4*)(Kb + row2 * D + h * 64 + hk0); rw = *(const u32x4*)(Rb + row2 * D + h * 64 + hk0); vw = *(const u32x2*)(Vb + row2 * D + h * 64 + 32 * half + 4 * j8); }
.Lrw3_hdir0:
	s_mul_i32 s16, s7, 0x1100
	v_lshlrev_b32_e32 v221, 4, v217
	s_lshl_b32 s17, s15, 6
	v_lshl_add_u32 v219, v217, 3, s17
	s_xor_b32 s18, s17, 64
	v_lshl_add_u32 v220, v217, 3, s18
	s_lshl_b32 s17, s15, 7
	v_mul_u32_u24_e32 v197, 0x110, v216
	v_add_u32_e32 v197, s17, v197
	v_lshl_add_u32 v222, v217, 4, v197
	v_lshl_add_u32 v223, v217, 5, v197
	s_lshl_b32 s17, s6, 7
	s_add_u32 s20, s26, 0xde00000
	s_addc_u32 s21, s27, 0
	s_add_u32 s20, s20, s17
	s_addc_u32 s21, s21, 0
	s_lshl_b32 s17, s8, 7
	s_add_u32 s22, s26, 0xbc00000
	s_addc_u32 s23, s27, 0
	s_add_u32 s22, s22, s17
	s_addc_u32 s23, s23, 0
	s_add_u32 s24, s26, 0x9a00000
	s_addc_u32 s25, s27, 0
	s_add_u32 s24, s24, s17
	s_addc_u32 s25, s25, 0
	s_lshl_b32 s18, s9, 6
	s_add_i32 s17, s17, s18
	s_lshl_b32 s18, s15, 5
	s_add_i32 s17, s17, s18
	s_add_u32 s42, s26, 0x5600000
	s_addc_u32 s43, s27, 0
	s_add_u32 s42, s42, s17
	s_addc_u32 s43, s43, 0
	s_lshl_b32 s17, s8, 2
	s_add_u32 s44, s26, 0xee00000
	s_addc_u32 s45, s27, 0
	s_add_u32 s44, s44, s17
	s_addc_u32 s45, s45, 0
	s_or_b32 s17, s9, s15
	s_cmp_eq_u32 s17, 0
	s_cselect_b32 s32, 1, 0
	s_load_dwordx2 s[46:47], s[0:1], 0x48
	s_load_dwordx2 s[48:49], s[0:1], 0x60
	s_load_dwordx2 s[50:51], s[0:1], 0x78
	s_load_dwordx2 s[52:53], s[0:1], 0x80
	s_load_dwordx2 s[54:55], s[0:1], 0x88
	s_lshl_b32 s17, s8, 8
	s_lshl_b32 s18, s15, 7
	s_add_i32 s19, s17, s18
	v_lshl_add_u32 v198, v217, 4, s19
	s_xor_b32 s18, s18, 128
	s_add_i32 s19, s17, s18
	v_lshl_add_u32 v199, v217, 4, s19
	s_waitcnt lgkmcnt(0)
	s_lshl_b32 s17, s6, 12
	s_add_u32 s46, s46, s17
	s_addc_u32 s47, s47, 0
	s_add_u32 s48, s48, s17
	s_addc_u32 s49, s49, 0
	s_add_u32 s46, s46, 0x2000
	s_addc_u32 s47, s47, 0
	s_add_u32 s48, s48, 0x2000
	s_addc_u32 s49, s49, 0
	s_add_u32 s50, s50, 0x1000
	s_addc_u32 s51, s51, 0
	s_add_u32 s52, s52, 0x1000
	s_addc_u32 s53, s53, 0
	s_add_u32 s54, s54, 0x1000
	s_addc_u32 s55, s55, 0
	global_load_dwordx4 v[32:35], v198, s[46:47] offset:0
	global_load_dwordx4 v[40:43], v198, s[48:49] offset:0
	global_load_dwordx4 v[64:67], v198, s[52:53] offset:0
	global_load_dwordx4 v[36:39], v198, s[46:47] offset:64
	global_load_dwordx4 v[44:47], v198, s[48:49] offset:64
	global_load_dwordx4 v[68:71], v198, s[52:53] offset:64
	global_load_dwordx4 v[48:51], v198, s[50:51] offset:0
	global_load_dwordx4 v[72:75], v198, s[54:55] offset:0
	global_load_dwordx4 v[52:55], v198, s[50:51] offset:64
	global_load_dwordx4 v[76:79], v198, s[54:55] offset:64
	global_load_dwordx4 v[56:59], v199, s[50:51] offset:0
	global_load_dwordx4 v[80:83], v199, s[54:55] offset:0
	global_load_dwordx4 v[60:63], v199, s[50:51] offset:64
	global_load_dwordx4 v[84:87], v199, s[54:55] offset:64
	s_lshl_b32 s17, s8, 6
	s_lshl_b32 s18, s15, 5
	s_add_i32 s17, s17, s18
	v_add_u32_e32 v200, s17, v196
	v_lshlrev_b32_e32 v200, 7, v200
	v_add_u32_e32 v200, v200, v221
	s_lshl_b32 s17, s6, 17
	s_add_u32 s46, s26, 0x200000
	s_addc_u32 s47, s27, 0
	s_add_u32 s46, s46, s17
	s_addc_u32 s47, s47, 0
	s_add_u32 s48, s46, 0x40000
	s_addc_u32 s49, s47, 0
	global_load_dwordx4 v[0:3], v200, s[46:47] offset:0
	global_load_dwordx4 v[16:19], v200, s[48:49] offset:0
	global_load_dwordx4 v[4:7], v200, s[46:47] offset:64
	global_load_dwordx4 v[20:23], v200, s[48:49] offset:64
	global_load_dwordx4 v[8:11], v200, s[46:47] offset:2048
	global_load_dwordx4 v[24:27], v200, s[48:49] offset:2048
	global_load_dwordx4 v[12:15], v200, s[46:47] offset:2112
	global_load_dwordx4 v[28:31], v200, s[48:49] offset:2112
	s_mov_b32 s10, 0
	s_mov_b32 s11, 0
	s_lshl_b32 s17, s10, 5
	s_cmp_lt_u32 s10, 8
	s_movk_i32 s18, 0x11ff
	s_cselect_b32 s18, 0xff, s18
	s_sub_i32 s18, s18, s17
	s_cmp_eq_u32 s6, 0
	s_cselect_b32 s17, s17, s18
	s_add_i32 s17, s17, s16
	v_add_u32_e32 v231, s17, v218
	v_lshl_add_u32 v226, v231, 9, v221
	v_lshl_add_u32 v227, v231, 11, v219
	v_lshl_add_u32 v228, v231, 11, v220
	v_lshlrev_b32_e32 v229, 3, v217
	v_lshl_add_u32 v229, v231, 11, v229
	v_lshlrev_b32_e32 v230, 6, v231
	global_load_dwordx4 v[88:91], v226, s[20:21]
	global_load_dwordx4 v[92:95], v226, s[20:21] offset:64
	global_load_dwordx4 v[96:99], v226, s[20:21] offset:256
	global_load_dwordx4 v[100:103], v226, s[20:21] offset:320
	global_load_dwordx2 v[104:105], v227, s[22:23] offset:0
	global_load_dwordx2 v[106:107], v227, s[22:23] offset:32
	global_load_dwordx2 v[108:109], v228, s[22:23] offset:0
	global_load_dwordx2 v[110:111], v228, s[22:23] offset:32
	global_load_dwordx2 v[112:113], v227, s[24:25] offset:0
	global_load_dwordx2 v[114:115], v227, s[24:25] offset:32
	global_load_dwordx2 v[116:117], v228, s[24:25] offset:0
	global_load_dwordx2 v[118:119], v228, s[24:25] offset:32
	global_load_dwordx2 v[120:121], v229, s[42:43]
	v_mov_b32_e32 v224, v222
	v_mov_b32_e32 v225, v223
	v_mov_b32_e32 v202, v230
	s_mov_b32 s89, 0
	s_mov_b32 s88, s32
	s_cmp_eq_u32 s89, 0
	s_cbranch_scc1 .Lrw3_hwall0
	s_waitcnt vmcnt(1)
	s_branch .Lrw3_hwdone0
